# ssm1 item: U-block gather loaded once per workgroup and shared through LDS, E loads double-buffered over 4 unrolled trips
# speedup vs baseline: 1.0172x; 1.0172x over previous
.LBB0_303:
	v_lshrrev_b32_e32 v18, 6, v188
	v_lshl_add_u64 v[134:135], s[94:95], 0, v[14:15]
	v_readfirstlane_b32 s0, v18
	v_add_co_u32_e32 v134, vcc, 0x6c00200, v134
	s_nop 1
	v_addc_co_u32_e32 v135, vcc, 0, v135, vcc
	s_mul_i32 s0, s0, 0xa000
	s_mov_b32 s1, 0
	s_mov_b64 s[98:99], 0x1400
	v_lshl_add_u64 v[134:135], v[134:135], 0, s[0:1]
	global_load_dwordx4 v[38:41], v[134:135], off
	v_lshl_add_u64 v[134:135], v[134:135], 0, s[98:99]
	global_load_dwordx4 v[42:45], v[134:135], off
	v_lshl_add_u64 v[134:135], v[134:135], 0, s[98:99]
	global_load_dwordx4 v[46:49], v[134:135], off
	v_lshl_add_u64 v[134:135], v[134:135], 0, s[98:99]
	global_load_dwordx4 v[50:53], v[134:135], off
	v_lshl_add_u64 v[134:135], v[134:135], 0, s[98:99]
	global_load_dwordx4 v[54:57], v[134:135], off
	v_lshl_add_u64 v[134:135], v[134:135], 0, s[98:99]
	global_load_dwordx4 v[58:61], v[134:135], off
	v_lshl_add_u64 v[134:135], v[134:135], 0, s[98:99]
	global_load_dwordx4 v[62:65], v[134:135], off
	v_lshl_add_u64 v[134:135], v[134:135], 0, s[98:99]
	global_load_dwordx4 v[66:69], v[134:135], off
	v_lshl_add_u64 v[22:23], s[94:95], 0, v[16:17]
	v_add_co_u32_e32 v18, vcc, 0x13a58000, v22
	s_nop 1
	v_addc_co_u32_e32 v19, vcc, 0, v23, vcc
	v_add_co_u32_e32 v22, vcc, 0x13a60000, v22
	s_nop 1
	v_addc_co_u32_e32 v23, vcc, 0, v23, vcc
	v_and_b32_e32 v136, 63, v188
	v_lshlrev_b32_e32 v136, 4, v136
	v_lshrrev_b32_e32 v137, 6, v188
	v_lshl_add_u32 v137, v137, 13, v136
	global_load_dwordx4 v[70:73], v[18:19], off offset:0
	global_load_dwordx4 v[102:105], v[22:23], off offset:0
	global_load_dwordx4 v[74:77], v[18:19], off offset:64
	global_load_dwordx4 v[106:109], v[22:23], off offset:64
	global_load_dwordx4 v[78:81], v[18:19], off offset:128
	global_load_dwordx4 v[110:113], v[22:23], off offset:128
	global_load_dwordx4 v[82:85], v[18:19], off offset:192
	global_load_dwordx4 v[114:117], v[22:23], off offset:192
	global_load_dwordx4 v[86:89], v[18:19], off offset:256
	global_load_dwordx4 v[118:121], v[22:23], off offset:256
	global_load_dwordx4 v[90:93], v[18:19], off offset:320
	global_load_dwordx4 v[122:125], v[22:23], off offset:320
	global_load_dwordx4 v[94:97], v[18:19], off offset:384
	global_load_dwordx4 v[126:129], v[22:23], off offset:384
	global_load_dwordx4 v[98:101], v[18:19], off offset:448
	global_load_dwordx4 v[130:133], v[22:23], off offset:448
	s_waitcnt vmcnt(23)
	ds_write_b128 v137, v[38:41] offset:0
	s_waitcnt vmcnt(22)
	ds_write_b128 v137, v[42:45] offset:1024
	s_waitcnt vmcnt(21)
	ds_write_b128 v137, v[46:49] offset:2048
	s_waitcnt vmcnt(20)
	ds_write_b128 v137, v[50:53] offset:3072
	s_waitcnt vmcnt(19)
	ds_write_b128 v137, v[54:57] offset:4096
	s_waitcnt vmcnt(18)
	ds_write_b128 v137, v[58:61] offset:5120
	s_waitcnt vmcnt(17)
	ds_write_b128 v137, v[62:65] offset:6144
	s_waitcnt vmcnt(16)
	ds_write_b128 v137, v[66:69] offset:7168
	s_waitcnt lgkmcnt(0)
	s_barrier
	ds_read_b128 v[138:141], v136 offset:0
	ds_read_b128 v[142:145], v136 offset:1024
	ds_read_b128 v[146:149], v136 offset:2048
	ds_read_b128 v[150:153], v136 offset:3072
	ds_read_b128 v[154:157], v136 offset:4096
	ds_read_b128 v[158:161], v136 offset:5120
	ds_read_b128 v[162:165], v136 offset:6144
	ds_read_b128 v[166:169], v136 offset:7168
	global_load_dwordx4 v[38:41], v[18:19], off offset:512
	global_load_dwordx4 v[214:217], v[22:23], off offset:512
	global_load_dwordx4 v[42:45], v[18:19], off offset:576
	global_load_dwordx4 v[218:221], v[22:23], off offset:576
	global_load_dwordx4 v[46:49], v[18:19], off offset:640
	global_load_dwordx4 v[222:225], v[22:23], off offset:640
	global_load_dwordx4 v[50:53], v[18:19], off offset:704
	global_load_dwordx4 v[226:229], v[22:23], off offset:704
	global_load_dwordx4 v[54:57], v[18:19], off offset:768
	global_load_dwordx4 v[230:233], v[22:23], off offset:768
	global_load_dwordx4 v[58:61], v[18:19], off offset:832
	global_load_dwordx4 v[234:237], v[22:23], off offset:832
	global_load_dwordx4 v[62:65], v[18:19], off offset:896
	global_load_dwordx4 v[238:241], v[22:23], off offset:896
	global_load_dwordx4 v[66:69], v[18:19], off offset:960
	global_load_dwordx4 v[242:245], v[22:23], off offset:960
	s_waitcnt vmcnt(30) lgkmcnt(7)
	v_mfma_f32_16x16x32_bf16 v[2:5], v[70:73], v[138:141], v[2:5]
	v_mfma_f32_16x16x32_bf16 v[6:9], v[102:105], v[138:141], v[6:9]
	s_waitcnt vmcnt(28) lgkmcnt(6)
	v_mfma_f32_16x16x32_bf16 v[2:5], v[74:77], v[142:145], v[2:5]
	v_mfma_f32_16x16x32_bf16 v[6:9], v[106:109], v[142:145], v[6:9]
	s_waitcnt vmcnt(26) lgkmcnt(5)
	v_mfma_f32_16x16x32_bf16 v[2:5], v[78:81], v[146:149], v[2:5]
	v_mfma_f32_16x16x32_bf16 v[6:9], v[110:113], v[146:149], v[6:9]
	s_waitcnt vmcnt(24) lgkmcnt(4)
	v_mfma_f32_16x16x32_bf16 v[2:5], v[82:85], v[150:153], v[2:5]
	v_mfma_f32_16x16x32_bf16 v[6:9], v[114:117], v[150:153], v[6:9]
	s_waitcnt vmcnt(22) lgkmcnt(3)
	v_mfma_f32_16x16x32_bf16 v[2:5], v[86:89], v[154:157], v[2:5]
	v_mfma_f32_16x16x32_bf16 v[6:9], v[118:121], v[154:157], v[6:9]
	s_waitcnt vmcnt(20) lgkmcnt(2)
	v_mfma_f32_16x16x32_bf16 v[2:5], v[90:93], v[158:161], v[2:5]
	v_mfma_f32_16x16x32_bf16 v[6:9], v[122:125], v[158:161], v[6:9]
	s_waitcnt vmcnt(18) lgkmcnt(1)
	v_mfma_f32_16x16x32_bf16 v[2:5], v[94:97], v[162:165], v[2:5]
	v_mfma_f32_16x16x32_bf16 v[6:9], v[126:129], v[162:165], v[6:9]
	s_waitcnt vmcnt(16) lgkmcnt(0)
	v_mfma_f32_16x16x32_bf16 v[2:5], v[98:101], v[166:169], v[2:5]
	v_mfma_f32_16x16x32_bf16 v[6:9], v[130:133], v[166:169], v[6:9]
	ds_read_b128 v[138:141], v136 offset:8192
	ds_read_b128 v[142:145], v136 offset:9216
	ds_read_b128 v[146:149], v136 offset:10240
	ds_read_b128 v[150:153], v136 offset:11264
	ds_read_b128 v[154:157], v136 offset:12288
	ds_read_b128 v[158:161], v136 offset:13312
	ds_read_b128 v[162:165], v136 offset:14336
	ds_read_b128 v[166:169], v136 offset:15360
	global_load_dwordx4 v[70:73], v[18:19], off offset:1024
	global_load_dwordx4 v[102:105], v[22:23], off offset:1024
	global_load_dwordx4 v[74:77], v[18:19], off offset:1088
	global_load_dwordx4 v[106:109], v[22:23], off offset:1088
	global_load_dwordx4 v[78:81], v[18:19], off offset:1152
	global_load_dwordx4 v[110:113], v[22:23], off offset:1152
	global_load_dwordx4 v[82:85], v[18:19], off offset:1216
	global_load_dwordx4 v[114:117], v[22:23], off offset:1216
	global_load_dwordx4 v[86:89], v[18:19], off offset:1280
	global_load_dwordx4 v[118:121], v[22:23], off offset:1280
	global_load_dwordx4 v[90:93], v[18:19], off offset:1344
	global_load_dwordx4 v[122:125], v[22:23], off offset:1344
	global_load_dwordx4 v[94:97], v[18:19], off offset:1408
	global_load_dwordx4 v[126:129], v[22:23], off offset:1408
	global_load_dwordx4 v[98:101], v[18:19], off offset:1472
	global_load_dwordx4 v[130:133], v[22:23], off offset:1472
	s_waitcnt vmcnt(30) lgkmcnt(7)
	v_mfma_f32_16x16x32_bf16 v[2:5], v[38:41], v[138:141], v[2:5]
	v_mfma_f32_16x16x32_bf16 v[6:9], v[214:217], v[138:141], v[6:9]
	s_waitcnt vmcnt(28) lgkmcnt(6)
	v_mfma_f32_16x16x32_bf16 v[2:5], v[42:45], v[142:145], v[2:5]
	v_mfma_f32_16x16x32_bf16 v[6:9], v[218:221], v[142:145], v[6:9]
	s_waitcnt vmcnt(26) lgkmcnt(5)
	v_mfma_f32_16x16x32_bf16 v[2:5], v[46:49], v[146:149], v[2:5]
	v_mfma_f32_16x16x32_bf16 v[6:9], v[222:225], v[146:149], v[6:9]
	s_waitcnt vmcnt(24) lgkmcnt(4)
	v_mfma_f32_16x16x32_bf16 v[2:5], v[50:53], v[150:153], v[2:5]
	v_mfma_f32_16x16x32_bf16 v[6:9], v[226:229], v[150:153], v[6:9]
	s_waitcnt vmcnt(22) lgkmcnt(3)
	v_mfma_f32_16x16x32_bf16 v[2:5], v[54:57], v[154:157], v[2:5]
	v_mfma_f32_16x16x32_bf16 v[6:9], v[230:233], v[154:157], v[6:9]
	s_waitcnt vmcnt(20) lgkmcnt(2)
	v_mfma_f32_16x16x32_bf16 v[2:5], v[58:61], v[158:161], v[2:5]
	v_mfma_f32_16x16x32_bf16 v[6:9], v[234:237], v[158:161], v[6:9]
	s_waitcnt vmcnt(18) lgkmcnt(1)
	v_mfma_f32_16x16x32_bf16 v[2:5], v[62:65], v[162:165], v[2:5]
	v_mfma_f32_16x16x32_bf16 v[6:9], v[238:241], v[162:165], v[6:9]
	s_waitcnt vmcnt(16) lgkmcnt(0)
	v_mfma_f32_16x16x32_bf16 v[2:5], v[66:69], v[166:169], v[2:5]
	v_mfma_f32_16x16x32_bf16 v[6:9], v[242:245], v[166:169], v[6:9]
	ds_read_b128 v[138:141], v136 offset:16384
	ds_read_b128 v[142:145], v136 offset:17408
	ds_read_b128 v[146:149], v136 offset:18432
	ds_read_b128 v[150:153], v136 offset:19456
	ds_read_b128 v[154:157], v136 offset:20480
	ds_read_b128 v[158:161], v136 offset:21504
	ds_read_b128 v[162:165], v136 offset:22528
	ds_read_b128 v[166:169], v136 offset:23552
	global_load_dwordx4 v[38:41], v[18:19], off offset:1536
	global_load_dwordx4 v[214:217], v[22:23], off offset:1536
	global_load_dwordx4 v[42:45], v[18:19], off offset:1600
	global_load_dwordx4 v[218:221], v[22:23], off offset:1600
	global_load_dwordx4 v[46:49], v[18:19], off offset:1664
	global_load_dwordx4 v[222:225], v[22:23], off offset:1664
	global_load_dwordx4 v[50:53], v[18:19], off offset:1728
	global_load_dwordx4 v[226:229], v[22:23], off offset:1728
	global_load_dwordx4 v[54:57], v[18:19], off offset:1792
	global_load_dwordx4 v[230:233], v[22:23], off offset:1792
	global_load_dwordx4 v[58:61], v[18:19], off offset:1856
	global_load_dwordx4 v[234:237], v[22:23], off offset:1856
	global_load_dwordx4 v[62:65], v[18:19], off offset:1920
	global_load_dwordx4 v[238:241], v[22:23], off offset:1920
	global_load_dwordx4 v[66:69], v[18:19], off offset:1984
	global_load_dwordx4 v[242:245], v[22:23], off offset:1984
	s_waitcnt vmcnt(30) lgkmcnt(7)
	v_mfma_f32_16x16x32_bf16 v[2:5], v[70:73], v[138:141], v[2:5]
	v_mfma_f32_16x16x32_bf16 v[6:9], v[102:105], v[138:141], v[6:9]
	s_waitcnt vmcnt(28) lgkmcnt(6)
	v_mfma_f32_16x16x32_bf16 v[2:5], v[74:77], v[142:145], v[2:5]
	v_mfma_f32_16x16x32_bf16 v[6:9], v[106:109], v[142:145], v[6:9]
	s_waitcnt vmcnt(26) lgkmcnt(5)
	v_mfma_f32_16x16x32_bf16 v[2:5], v[78:81], v[146:149], v[2:5]
	v_mfma_f32_16x16x32_bf16 v[6:9], v[110:113], v[146:149], v[6:9]
	s_waitcnt vmcnt(24) lgkmcnt(4)
	v_mfma_f32_16x16x32_bf16 v[2:5], v[82:85], v[150:153], v[2:5]
	v_mfma_f32_16x16x32_bf16 v[6:9], v[114:117], v[150:153], v[6:9]
	s_waitcnt vmcnt(22) lgkmcnt(3)
	v_mfma_f32_16x16x32_bf16 v[2:5], v[86:89], v[154:157], v[2:5]
	v_mfma_f32_16x16x32_bf16 v[6:9], v[118:121], v[154:157], v[6:9]
	s_waitcnt vmcnt(20) lgkmcnt(2)
	v_mfma_f32_16x16x32_bf16 v[2:5], v[90:93], v[158:161], v[2:5]
	v_mfma_f32_16x16x32_bf16 v[6:9], v[122:125], v[158:161], v[6:9]
	s_waitcnt vmcnt(18) lgkmcnt(1)
	v_mfma_f32_16x16x32_bf16 v[2:5], v[94:97], v[162:165], v[2:5]
	v_mfma_f32_16x16x32_bf16 v[6:9], v[126:129], v[162:165], v[6:9]
	s_waitcnt vmcnt(16) lgkmcnt(0)
	v_mfma_f32_16x16x32_bf16 v[2:5], v[98:101], v[166:169], v[2:5]
	v_mfma_f32_16x16x32_bf16 v[6:9], v[130:133], v[166:169], v[6:9]
	ds_read_b128 v[138:141], v136 offset:24576
	ds_read_b128 v[142:145], v136 offset:25600
	ds_read_b128 v[146:149], v136 offset:26624
	ds_read_b128 v[150:153], v136 offset:27648
	ds_read_b128 v[154:157], v136 offset:28672
	ds_read_b128 v[158:161], v136 offset:29696
	ds_read_b128 v[162:165], v136 offset:30720
	ds_read_b128 v[166:169], v136 offset:31744
	s_waitcnt vmcnt(14) lgkmcnt(7)
	v_mfma_f32_16x16x32_bf16 v[2:5], v[38:41], v[138:141], v[2:5]
	v_mfma_f32_16x16x32_bf16 v[6:9], v[214:217], v[138:141], v[6:9]
	s_waitcnt vmcnt(12) lgkmcnt(6)
	v_mfma_f32_16x16x32_bf16 v[2:5], v[42:45], v[142:145], v[2:5]
	v_mfma_f32_16x16x32_bf16 v[6:9], v[218:221], v[142:145], v[6:9]
	s_waitcnt vmcnt(10) lgkmcnt(5)
	v_mfma_f32_16x16x32_bf16 v[2:5], v[46:49], v[146:149], v[2:5]
	v_mfma_f32_16x16x32_bf16 v[6:9], v[222:225], v[146:149], v[6:9]
	s_waitcnt vmcnt(8) lgkmcnt(4)
	v_mfma_f32_16x16x32_bf16 v[2:5], v[50:53], v[150:153], v[2:5]
	v_mfma_f32_16x16x32_bf16 v[6:9], v[226:229], v[150:153], v[6:9]
	s_waitcnt vmcnt(6) lgkmcnt(3)
	v_mfma_f32_16x16x32_bf16 v[2:5], v[54:57], v[154:157], v[2:5]
	v_mfma_f32_16x16x32_bf16 v[6:9], v[230:233], v[154:157], v[6:9]
	s_waitcnt vmcnt(4) lgkmcnt(2)
	v_mfma_f32_16x16x32_bf16 v[2:5], v[58:61], v[158:161], v[2:5]
	v_mfma_f32_16x16x32_bf16 v[6:9], v[234:237], v[158:161], v[6:9]
	s_waitcnt vmcnt(2) lgkmcnt(1)
	v_mfma_f32_16x16x32_bf16 v[2:5], v[62:65], v[162:165], v[2:5]
	v_mfma_f32_16x16x32_bf16 v[6:9], v[238:241], v[162:165], v[6:9]
	s_waitcnt vmcnt(0) lgkmcnt(0)
	v_mfma_f32_16x16x32_bf16 v[2:5], v[66:69], v[166:169], v[2:5]
	v_mfma_f32_16x16x32_bf16 v[6:9], v[242:245], v[166:169], v[6:9]
	s_nop 7
	v_lshl_add_u32 v0, v11, 5, s3
	v_or_b32_e32 v0, s2, v0
	v_ashrrev_i32_e32 v11, 31, v10
	v_mad_i64_i32 v[10:11], s[0:1], v0, 36, v[10:11]
	v_readlane_b32 s0, v253, 40
	v_lshlrev_b64 v[10:11], 9, v[10:11]
	v_readlane_b32 s1, v253, 41
	v_ashrrev_i32_e32 v13, 31, v12
	v_lshlrev_b32_e32 v0, 4, v24
	v_lshl_add_u64 v[10:11], s[0:1], 0, v[10:11]
	v_lshl_add_u64 v[10:11], v[12:13], 2, v[10:11]
	v_lshl_add_u64 v[10:11], v[10:11], 0, v[0:1]
	s_mov_b64 s[34:35], 0
	global_store_dwordx4 v[10:11], v[2:5], off
	global_store_dwordx4 v[10:11], v[6:9], off offset:64
